# conversion quotas: prologue 4096 (two items per wave), G1 4354, G3 7848; last G1 slot ends at N_ALL
# baseline (speedup 1.0000x reference)
; #define PHASE_IDS() int tid = threadIdx.x; asm volatile("" : "+v"(tid)); const int lane = tid & 63, wid = __builtin_amdgcn_readfirstlane(tid >> 6), gw = bx * NWAVES + wid; (void)lane; (void)gw
; __device__ __forceinline__ void convert_items(const Args& A, unsigned char* ws, int g0, int g1, int w, int nw, float* scr, int lane) {
;     for (int it = g0 + w; it < g1; it += nw) {
; __global__ void __launch_bounds__(NWAVES * 64, 2) fwd_kernel(Args A) {
;     ...
;     {
;         PHASE_IDS();
;         float* scr = (float*)(lds + wid * TSCR);
;         const bool lazy = (G == 256);
;         convert_items(A, ws, 0, lazy ? Q_P : N_ALL, gw, NGW, scr, lane);
;         prologue_rows(A.x, XB, SS + (size_t)SS_Q1 * SEQ, gw, NGW, lane);
.LBB0_6:
	s_or_b64 exec, exec, s[4:5]
	s_load_dwordx16 s[40:55], s[0:1], 0x0
	s_load_dwordx16 s[68:83], s[0:1], 0x40
	s_load_dword s14, s[0:1], 0x98
	s_add_i32 s0, 0, 0x23ff8
	v_mov_b32_e32 v1, s0
	s_lshl_b32 s0, s84, 3
	v_writelane_b32 v250, s0, 7
	v_mov_b32_e32 v2, v204
	s_waitcnt lgkmcnt(0)
	s_barrier
	ds_read_b32 v1, v1
	v_writelane_b32 v250, s1, 8
	s_mov_b32 s1, 0
	v_readfirstlane_b32 s0, v2
	s_ashr_i32 s18, s0, 6
	v_readlane_b32 s0, v250, 0
	s_lshl_b32 s0, s0, 3
	s_add_i32 s15, s18, s0
	s_cmpk_lg_i32 s84, 0x100
	v_writelane_b32 v250, s0, 9
	s_cselect_b64 s[4:5], -1, 0
	v_writelane_b32 v250, s4, 10
	s_cmpk_eq_i32 s84, 0x100
	s_cselect_b64 s[30:31], -1, 0
	v_writelane_b32 v250, s5, 11
	v_writelane_b32 v250, s40, 12
	s_movk_i32 s0, 0x1000
	s_and_b64 s[4:5], s[30:31], exec
	v_writelane_b32 v250, s41, 13
	v_writelane_b32 v250, s42, 14
	v_writelane_b32 v250, s43, 15
	v_writelane_b32 v250, s44, 16
	v_writelane_b32 v250, s45, 17
	v_writelane_b32 v250, s46, 18
	v_writelane_b32 v250, s47, 19
	v_writelane_b32 v250, s48, 20
	v_writelane_b32 v250, s49, 21
	v_writelane_b32 v250, s50, 22
	v_writelane_b32 v250, s51, 23
	v_writelane_b32 v250, s52, 24
	v_writelane_b32 v250, s53, 25
	v_writelane_b32 v250, s54, 26
	v_writelane_b32 v250, s55, 27
	v_writelane_b32 v250, s86, 28
	s_cselect_b32 s19, s0, 0xb000
	s_waitcnt lgkmcnt(0)
	v_readfirstlane_b32 s33, v1
	v_writelane_b32 v250, s87, 29
	v_writelane_b32 v250, s68, 30
	s_cmp_ge_i32 s15, s19
	v_and_b32_e32 v1, 63, v2
	v_writelane_b32 v250, s69, 31
	v_writelane_b32 v250, s70, 32
	v_writelane_b32 v250, s71, 33
	v_writelane_b32 v250, s72, 34
	v_writelane_b32 v250, s73, 35
	v_writelane_b32 v250, s74, 36
	v_writelane_b32 v250, s75, 37
	v_writelane_b32 v250, s76, 38
	v_writelane_b32 v250, s77, 39
	v_writelane_b32 v250, s78, 40
	v_writelane_b32 v250, s79, 41
	v_writelane_b32 v250, s80, 42
	v_writelane_b32 v250, s81, 43
	v_writelane_b32 v250, s82, 44
	v_writelane_b32 v250, s83, 45
	s_cbranch_scc1 .LBB0_40
	s_mul_i32 s0, s18, 0x4100
	s_add_i32 s0, s0, 0
	s_add_u32 s20, s86, 0x10a00000
	s_addc_u32 s21, s87, 0
	s_add_u32 s22, s86, 0x5a00000
	s_addc_u32 s23, s87, 0
	s_add_u32 s24, s86, 0x3a00000
	v_lshlrev_b32_e32 v3, 2, v1
	s_addc_u32 s25, s87, 0
	v_lshrrev_b32_e32 v13, 4, v1
	v_and_b32_e32 v4, 60, v3
	s_add_u32 s26, s86, 0x200000
	v_lshlrev_b32_e32 v3, 2, v4
	v_mul_u32_u24_e32 v5, 0x104, v13
	v_and_b32_e32 v2, 7, v2
	v_lshrrev_b32_e32 v19, 3, v1
	s_addc_u32 s27, s87, 0
	v_add3_u32 v18, s0, v3, v5
	v_lshlrev_b32_e32 v12, 3, v2
	v_mul_u32_u24_e32 v2, 0x820, v2
	v_lshlrev_b32_e32 v3, 2, v19
	s_cmp_lg_u64 s[78:79], 0
	v_add3_u32 v20, s0, v2, v3
	s_cselect_b64 s[4:5], -1, 0
	s_cmp_lg_u64 s[44:45], 0
	v_readlane_b32 s8, v250, 7
	v_mov_b32_e32 v11, 0
	v_or_b32_e32 v21, 8, v19
	v_or_b32_e32 v22, 16, v19
	v_or_b32_e32 v23, 24, v19
	v_or_b32_e32 v24, 32, v19
	v_or_b32_e32 v25, 40, v19
	v_or_b32_e32 v26, 48, v19
	v_or_b32_e32 v27, 56, v19
	s_cselect_b64 s[6:7], -1, 0
	s_lshl_b32 s28, s15, 6
	s_lshl_b32 s29, s8, 6
	s_lshl_b32 s34, s15, 1
	s_lshl_b32 s35, s8, 1
	s_mov_b32 s75, 0x8000
	s_mov_b32 s76, 0x10000
	s_mov_b32 s77, 0x18000
	s_mov_b32 s78, 0x20000
	s_mov_b32 s79, 0x28000
	s_mov_b32 s80, 0x30000
	s_mov_b32 s81, 0x38000
	s_mov_b32 s82, 0x40000
	s_mov_b32 s83, 0x48000
	s_mov_b32 s87, 0x50000
	s_mov_b32 s88, 0x58000
	s_mov_b32 s89, 0x60000
	s_mov_b32 s90, 0x68000
	s_mov_b32 s91, 0x70000
	s_mov_b32 s52, 0x78000
	v_add_u32_e32 v28, 0x410, v18
	v_add_u32_e32 v29, 0x418, v18
	v_add_u32_e32 v30, 0x820, v18
	v_add_u32_e32 v31, 0x828, v18
	v_add_u32_e32 v32, 0xc30, v18
	v_add_u32_e32 v33, 0xc38, v18
	v_add_u32_e32 v34, 0x1040, v18
	v_add_u32_e32 v35, 0x1048, v18
	v_add_u32_e32 v36, 0x1450, v18
	v_add_u32_e32 v37, 0x1458, v18
	v_add_u32_e32 v38, 0x1860, v18
	v_add_u32_e32 v39, 0x1868, v18
	v_add_u32_e32 v40, 0x1c70, v18
	v_add_u32_e32 v41, 0x1c78, v18
	v_add_u32_e32 v42, 0x2080, v18
	v_add_u32_e32 v43, 0x2088, v18
	v_add_u32_e32 v44, 0x2490, v18
	v_add_u32_e32 v45, 0x2498, v18
	v_add_u32_e32 v46, 0x28a0, v18
	v_add_u32_e32 v47, 0x28a8, v18
	v_add_u32_e32 v48, 0x2cb0, v18
	v_add_u32_e32 v49, 0x2cb8, v18
	v_add_u32_e32 v50, 0x30c0, v18
	v_add_u32_e32 v51, 0x30c8, v18
	v_add_u32_e32 v52, 0x34d0, v18
	v_add_u32_e32 v53, 0x34d8, v18
	v_add_u32_e32 v54, 0x38e0, v18
	v_add_u32_e32 v55, 0x38e8, v18
	v_add_u32_e32 v56, 0x3cf0, v18
	v_add_u32_e32 v57, 0x3cf8, v18
	s_mov_b32 s53, 0x16000
	s_mov_b32 s54, 0x2c000
	s_mov_b32 s55, 0x42000
	s_mov_b32 s56, 0x6e000
	s_mov_b32 s57, 0x84000
	s_mov_b32 s58, 0x9a000
	s_mov_b32 s59, 0xb0000
	v_lshlrev_b32_e32 v10, 2, v4
	v_lshlrev_b32_e32 v14, 1, v12
	v_add_u32_e32 v58, 0x400, v20
	s_mov_b32 s60, 0xc6000
	s_mov_b32 s61, 0xdc000
	s_mov_b32 s62, 0xf2000
	s_mov_b32 s63, 0x108000
	s_mov_b32 s64, 0x11e000
	s_mov_b32 s65, 0x134000
	s_mov_b32 s66, 0x14a000
	s_mov_b32 s67, s15
	v_readlane_b32 s9, v250, 8
	s_branch .LBB0_11

; __device__ __forceinline__ unsigned xb_ld(unsigned* p)              { return __hip_atomic_load(p, __ATOMIC_RELAXED, __HIP_MEMORY_SCOPE_AGENT); }
; #define PHASE_IDS() int tid = threadIdx.x; asm volatile("" : "+v"(tid)); const int lane = tid & 63, wid = __builtin_amdgcn_readfirstlane(tid >> 6), gw = bx * NWAVES + wid; (void)lane; (void)gw
; __global__ void __launch_bounds__(NWAVES * 64, 2) fwd_kernel(Args A) {
;     ...
;     bool tp = (G == 256);
;     if (tp) { for (unsigned q = 0; q < 16; ++q) { const unsigned c = xb_ld(&barw[XB_XCNT(q)]); tp = tp && (c == (q < 8 ? 32u : 0u)); } }
;     tp = __builtin_amdgcn_readfirstlane((int)tp) != 0;
;     const int vc = tp ? (int)(my_r * 8u + my_x) : bx;
;     ...
; #pragma nounroll
;     for (int l = 0; l < DEPTH; ++l) {
;         { pg8::Gemm g{XB, (const bf16*)(ws + WS_WIN + l * SZ_WIN), SEQ, INW, DM};
;           pg8::EpiZ E{Z, INW, 8, SS + (size_t)(SS_Q1 + l) * SEQ};
;           if (G == 256) { pg8::OrderTok S{vc, INW / 256, 0}; pg8::gemm_phase<pg8::EpiZ, pg8::OrderTok, true, true>(ldsl, g, S, E); }
;           else { pg8::StaticOrder S; S.init(SEQ, INW, G, bx); pg8::gemm_phase<pg8::EpiZ, pg8::StaticOrder, true, true>(ldsl, g, S, E); } }
;         if (G == 256 && vc >= 192) {
;             PHASE_IDS(); const int g0 = Q_P + l * (Q_G1 + Q_G3), g1 = g0 + Q_G1;
;             convert_items(A, ws, g0 < N_ALL ? g0 : N_ALL, g1 < N_ALL ? g1 : N_ALL, (vc - 192) * NWAVES + wid, 64 * NWAVES, (float*)(lds + wid * TSCR), lane); }
.LBB0_111:
	s_add_u32 s64, s86, 0x16200000
	s_addc_u32 s65, s87, 0
	s_add_u32 s80, s86, 0x10000
	s_addc_u32 s2, s87, 0
	s_add_u32 s82, s86, 0x18200000
	s_addc_u32 s83, s87, 0
	s_add_u32 s18, s86, 0x1ba00000
	s_addc_u32 s19, s87, 0
	s_add_u32 s20, s86, 0x1da00000
	v_cndmask_b32_e64 v0, 0, 1, s[0:1]
	s_addc_u32 s21, s87, 0
	v_readfirstlane_b32 s0, v0
	s_lshl_b32 s1, s33, 3
	s_and_b32 s0, 1, s0
	s_add_i32 s4, s1, s17
	s_cmp_eq_u32 s0, 1
	v_writelane_b32 v250, s2, 46
	s_cselect_b64 s[0:1], -1, 0
	s_and_b64 s[2:3], s[0:1], exec
	v_readlane_b32 s28, v250, 0
	s_cselect_b32 s3, s4, s28
	s_xor_b64 s[0:1], s[0:1], -1
	v_writelane_b32 v250, s0, 47
	v_mov_b32_e32 v2, 0
	v_mov_b32_e32 v205, 0x358637bd
	v_writelane_b32 v250, s1, 48
	s_add_u32 s0, s86, 0x200000
	v_writelane_b32 v250, s0, 49
	s_addc_u32 s0, s87, 0
	s_cmpk_lt_i32 s28, 0x1c0
	v_writelane_b32 v250, s0, 50
	s_cselect_b64 s[0:1], -1, 0
	v_writelane_b32 v250, s0, 51
	s_bfe_u32 s4, s3, 0x20003
	s_ashr_i32 s22, s3, 5
	v_writelane_b32 v250, s1, 52
	s_ashr_i32 s0, s28, 31
	v_writelane_b32 v250, s0, 53
	s_lshr_b32 s0, s0, 29
	s_add_i32 s0, s28, s0
	s_ashr_i32 s5, s0, 3
	s_and_b32 s0, s0, -8
	s_sub_i32 s6, s28, s0
	s_ashr_i32 s0, s84, 31
	v_writelane_b32 v250, s0, 54
	s_lshl_b32 s0, s3, 2
	s_and_b32 s0, s0, 28
	s_or_b32 s7, s0, s4
	s_cmp_lt_i32 s22, 14
	s_cselect_b64 s[0:1], -1, 0
	s_ashr_i32 s23, s22, 31
	v_writelane_b32 v250, s0, 55
	s_lshl_b32 s10, s7, 20
	s_lshl_b64 s[24:25], s[22:23], 20
	v_writelane_b32 v250, s1, 56
	s_add_u32 s0, s64, s10
	s_addc_u32 s1, s65, 0
	s_add_u32 s8, s0, 0x80000
	s_addc_u32 s9, s1, 0
	s_lshl_b32 s2, s7, 8
	v_writelane_b32 v250, s8, 57
	s_cmpk_gt_i32 s3, 0xbf
	s_mul_i32 s7, s7, 0x2c0000
	v_writelane_b32 v250, s9, 58
	s_cselect_b64 s[8:9], -1, 0
	v_writelane_b32 v250, s2, 59
	s_and_b64 s[8:9], s[30:31], s[8:9]
	v_writelane_b32 v250, s8, 60
	s_lshl_b32 s11, s3, 3
	s_add_i32 s2, s11, 0xa00
	v_writelane_b32 v250, s9, 61
	v_writelane_b32 v250, s2, 62
	s_add_u32 s2, s86, 0x10a00000
	v_writelane_b32 v250, s2, 63
	s_addc_u32 s2, s87, 0
	v_writelane_b32 v249, s2, 0
	s_add_u32 s2, s86, 0x5a00000
	v_writelane_b32 v249, s2, 1
	s_addc_u32 s2, s87, 0
	v_writelane_b32 v249, s2, 2
	s_add_u32 s2, s86, 0x3a00000
	v_writelane_b32 v249, s2, 3
	s_addc_u32 s2, s87, 0
	s_cmp_lg_u64 s[78:79], 0
	v_writelane_b32 v249, s2, 4
	s_cselect_b64 s[8:9], -1, 0
	v_writelane_b32 v249, s8, 5
	s_cmp_lg_u64 s[44:45], 0
	v_mov_b32_e32 v206, 0x260
	v_writelane_b32 v249, s9, 6
	s_cselect_b64 s[8:9], -1, 0
	v_writelane_b32 v249, s8, 7
	v_mov_b32_e32 v207, 1
	v_mbcnt_hi_u32_b32 v208, -1, v40
	v_writelane_b32 v249, s9, 8
	s_add_u32 s8, s86, 0x200
	s_addc_u32 s9, s87, 0
	v_writelane_b32 v249, s8, 9
	v_mov_b64_e32 v[160:161], 0x1c0
	v_mov_b64_e32 v[162:163], 0x1bf
	v_writelane_b32 v249, s9, 10
	s_add_u32 s8, s86, 0x1000
	s_addc_u32 s9, s87, 0
	v_writelane_b32 v249, s8, 11
	v_mov_b32_e32 v209, 0x41b17218
	v_mov_b32_e32 v210, 0x1a00
	v_writelane_b32 v249, s9, 12
	s_add_u32 s8, s86, 0x1100
	s_addc_u32 s9, s87, 0
	v_writelane_b32 v249, s8, 13
	v_mov_b32_e32 v211, 0x1800
	v_mov_b64_e32 v[164:165], 0x100
	v_writelane_b32 v249, s9, 14
	s_add_u32 s8, s86, 0x1200
	s_addc_u32 s9, s87, 0
	v_writelane_b32 v249, s8, 15
	v_mov_b64_e32 v[166:167], 0xff
	v_mov_b64_e32 v[168:169], 0x580
	v_writelane_b32 v249, s9, 16
	s_add_u32 s8, s86, 0x1300
	s_addc_u32 s9, s87, 0
	v_writelane_b32 v249, s8, 17
	s_cmp_eq_u32 s17, 15
	v_mov_b64_e32 v[170:171], 0x57f
	v_writelane_b32 v249, s9, 18
	s_cselect_b64 s[8:9], -1, 0
	v_writelane_b32 v249, s8, 19
	s_cmp_eq_u32 s17, 14
	s_mov_b32 s97, 0xf800000
	v_writelane_b32 v249, s9, 20
	s_cselect_b64 s[8:9], -1, 0
	v_writelane_b32 v249, s8, 21
	s_cmp_eq_u32 s17, 13
	s_movk_i32 s33, 0x90
	v_writelane_b32 v249, s9, 22
	s_cselect_b64 s[8:9], -1, 0
	v_writelane_b32 v249, s8, 23
	s_cmp_eq_u32 s17, 12
	s_mov_b32 s72, 0x3e38aa3b
	v_writelane_b32 v249, s9, 24
	s_cselect_b64 s[8:9], -1, 0
	v_writelane_b32 v249, s8, 25
	s_cmp_eq_u32 s17, 11
	s_mov_b32 s54, 0
	v_writelane_b32 v249, s9, 26
	s_cselect_b64 s[8:9], -1, 0
	v_writelane_b32 v249, s8, 27
	s_cmp_eq_u32 s17, 10
	s_mov_b32 s77, 0
	v_writelane_b32 v249, s9, 28
	s_cselect_b64 s[8:9], -1, 0
	v_writelane_b32 v249, s8, 29
	s_cmp_eq_u32 s17, 9
	s_mov_b32 s90, 0x3e6d3388
	v_writelane_b32 v249, s9, 30
	s_cselect_b64 s[8:9], -1, 0
	v_writelane_b32 v249, s8, 31
	s_cmp_eq_u32 s17, 8
	s_mov_b32 s92, 0x3f07dc22
	v_writelane_b32 v249, s9, 32
	s_cselect_b64 s[8:9], -1, 0
	v_writelane_b32 v249, s8, 33
	s_cmp_eq_u32 s17, 7
	s_mov_b32 s94, 0x3f35f0e3
	v_writelane_b32 v249, s9, 34
	s_cselect_b64 s[8:9], -1, 0
	v_writelane_b32 v249, s8, 35
	s_cmp_eq_u32 s17, 6
	s_mov_b32 s96, 0xbe11a98e
	v_writelane_b32 v249, s9, 36
	s_cselect_b64 s[8:9], -1, 0
	v_writelane_b32 v249, s8, 37
	s_cmp_eq_u32 s17, 5
	s_nop 0
	v_writelane_b32 v249, s9, 38
	s_cselect_b64 s[8:9], -1, 0
	v_writelane_b32 v249, s8, 39
	s_cmp_eq_u32 s17, 4
	s_nop 0
	v_writelane_b32 v249, s9, 40
	s_cselect_b64 s[8:9], -1, 0
	v_writelane_b32 v249, s8, 41
	s_cmp_eq_u32 s17, 3
	s_nop 0
	v_writelane_b32 v249, s9, 42
	s_cselect_b64 s[8:9], -1, 0
	v_writelane_b32 v249, s8, 43
	s_cmp_eq_u32 s17, 2
	s_nop 0
	v_writelane_b32 v249, s9, 44
	s_cselect_b64 s[8:9], -1, 0
	v_writelane_b32 v249, s8, 45
	s_cmp_eq_u32 s17, 1
	s_nop 0
	v_writelane_b32 v249, s9, 46
	s_cselect_b64 s[8:9], -1, 0
	v_writelane_b32 v249, s8, 47
	s_cmp_eq_u32 s17, 0
	s_nop 0
	v_writelane_b32 v249, s9, 48
	s_cselect_b64 s[8:9], -1, 0
	v_writelane_b32 v249, s8, 49
	s_lshl_b32 s2, s17, 8
	s_nop 0
	v_writelane_b32 v249, s9, 50
	s_add_u32 s8, s86, s2
	s_addc_u32 s9, s87, 0
	s_add_u32 s12, s8, 0x1400
	s_addc_u32 s13, s9, 0
	v_writelane_b32 v249, s12, 51
	s_nop 1
; __device__ __forceinline__ void mixer_phase256(const Args& A, int l, int vc, const bf16* Z, bf16* MIX, ss_t* ssa, ss_t* ssb, unsigned char* lds, int tid, int wid, int lane) {
;     ...
;     const int gx = vc & 7, gj = vc >> 3;
;     const int n = 8 * gx + (gj >> 2), kvh = gj & 3, h = gj & 15, cb = 8 * gx + 4 * (gj >> 4);
;     const int fr = lane & 15, fq = lane >> 4;
;     const bool isK = tid < 256; const int arow = tid & 255; const int atok = (n - 1) * 128 + arow;
;     u32x4 aw[8], sw[8];
;     { const bf16* ap = Z + (size_t)(atok < 0 ? 0 : atok) * INW + (isK ? KCOL : VCOL) + kvh * 64;
; #pragma unroll
;       for (int c = 0; c < 8; ++c) aw[c] = *(const u32x4*)(ap + 8 * c); }
;     const int srow = tid & 127, sj = tid >> 7;
;     { const bf16* sp = Z + (size_t)((cb + sj) * 128 + srow) * INW + 1024 + h * 64;
; #pragma unroll
;       for (int c = 0; c < 8; ++c) sw[c] = *(const u32x4*)(sp + 8 * c); }
;     const int st = 16 * wid + fr; const int nks = (wid >> 1) + 1;
	v_writelane_b32 v249, s13, 52
	s_add_u32 s12, s8, 0x2400
	s_addc_u32 s13, s9, 0
	v_writelane_b32 v249, s12, 53
	s_nop 1
	v_writelane_b32 v249, s13, 54
	s_add_u32 s12, s86, 0x3400
	s_addc_u32 s13, s87, 0
	v_writelane_b32 v249, s12, 55
	s_nop 1
	v_writelane_b32 v249, s13, 56
	s_add_u32 s12, s86, 0x3500
	s_addc_u32 s13, s87, 0
	v_writelane_b32 v249, s12, 57
	s_cmpk_lt_i32 s28, 0x100
	s_nop 0
	v_writelane_b32 v249, s13, 58
	s_cselect_b64 s[12:13], -1, 0
	v_writelane_b32 v249, s12, 59
	s_cmpk_lt_i32 s28, 0x400
	s_nop 0
	v_writelane_b32 v249, s13, 60
	s_cselect_b64 s[12:13], -1, 0
	v_writelane_b32 v249, s12, 61
	s_and_b32 s2, s11, 56
	s_nop 0
	v_writelane_b32 v249, s13, 62
	s_and_b32 s12, s22, -4
	s_add_i32 s14, s2, s12
	s_add_i32 s12, s2, s22
	s_ashr_i32 s2, s3, 3
	s_and_b32 s13, s2, 3
	s_and_b32 s17, s2, 15
	s_lshl_b32 s2, s13, 6
	s_lshl_b32 s23, s13, 2
	s_lshl_b32 s13, s13, 8
	v_writelane_b32 v248, s13, 0
	s_lshl_b32 s13, s12, 7
	v_writelane_b32 v248, s13, 1
	s_addk_i32 s13, 0xff80
	v_writelane_b32 v248, s13, 2
	s_lshl_b32 s13, s17, 7
	s_add_u32 s26, s82, s13
	v_writelane_b32 v248, s17, 3
	s_addc_u32 s27, s83, 0
	v_writelane_b32 v248, s26, 4
	v_writelane_b32 v249, s23, 63
	s_nop 0
	v_writelane_b32 v248, s27, 5
	v_writelane_b32 v248, s14, 6
	s_lshl_b32 s14, s14, 7
	s_or_b32 s17, s14, 0x80
	v_writelane_b32 v248, s17, 7
	s_or_b32 s17, s14, 0x100
	v_writelane_b32 v248, s17, 8
	v_writelane_b32 v248, s14, 9
	s_or_b32 s14, s14, 0x180
	s_add_u32 s26, s18, s13
	v_writelane_b32 v248, s14, 10
	s_addc_u32 s27, s19, 0
	v_writelane_b32 v248, s26, 11
	s_cmp_gt_i32 s12, 0
	s_cselect_b64 s[12:13], -1, 0
	v_writelane_b32 v248, s27, 12
	v_writelane_b32 v248, s12, 13
	s_nop 1
	v_writelane_b32 v248, s13, 14
	s_add_u32 s12, s8, 0x4000
	s_addc_u32 s13, s9, 0
	v_writelane_b32 v248, s12, 15
	s_add_u32 s8, s8, 0x5000
	s_addc_u32 s9, s9, 0
	v_writelane_b32 v248, s13, 16
	s_lshl_b32 s12, s6, 5
	v_writelane_b32 v248, s8, 17
	s_cmp_lt_i32 s22, 8
	s_nop 0
	v_writelane_b32 v248, s9, 18
	s_cselect_b64 s[8:9], -1, 0
	s_add_u32 s88, s18, s10
	v_writelane_b32 v248, s8, 19
	s_addc_u32 s89, s19, 0
	s_nop 0
	v_writelane_b32 v248, s9, 20
	s_add_u32 s8, s88, 0x80000
	s_addc_u32 s9, s89, 0
	v_writelane_b32 v248, s8, 21
	s_cmpk_lt_i32 s28, 0x580
	s_mov_b64 s[28:29], 0x80
	v_writelane_b32 v248, s9, 22
	s_cselect_b64 s[8:9], -1, 0
	v_writelane_b32 v248, s8, 23
	s_add_i32 s26, s22, 32
	s_cmp_lt_i32 s22, 12
	v_writelane_b32 v248, s9, 24
	s_mov_b32 s8, s22
	v_writelane_b32 v248, s8, 25
	s_nop 1
	v_writelane_b32 v248, s9, 26
	s_cselect_b64 s[8:9], -1, 0
	v_writelane_b32 v248, s8, 27
	s_ashr_i32 s27, s26, 31
	s_nop 0
	v_writelane_b32 v248, s9, 28
	s_mov_b32 s8, s26
	v_writelane_b32 v248, s8, 29
	s_nop 1
	v_writelane_b32 v248, s9, 30
	s_lshl_b64 s[8:9], s[26:27], 20
	v_writelane_b32 v248, s8, 31
	s_cmpk_gt_i32 s3, 0x7f
	s_nop 0
	v_writelane_b32 v248, s9, 32
	s_cselect_b64 s[8:9], -1, 0
	s_and_b64 s[8:9], s[30:31], s[8:9]
	v_writelane_b32 v248, s8, 33
	s_mov_b32 s30, 0x3e027906
	s_nop 0
	v_writelane_b32 v248, s9, 34
	s_add_i32 s8, s11, 0x1d02
	s_add_u32 s34, s20, s7
	s_addc_u32 s35, s21, 0
	v_writelane_b32 v248, s8, 35
	s_add_u32 s8, s34, 0x160000
	s_addc_u32 s9, s35, 0
	v_writelane_b32 v248, s8, 36
	s_cmp_lt_i32 s6, 0
	s_mul_i32 s7, s6, 33
	v_writelane_b32 v248, s9, 37
	s_cselect_b32 s8, 57, 56
	s_mul_i32 s8, s6, s8
	s_movk_i32 s9, 0xb1
	s_cselect_b32 s7, s7, s12
	s_cselect_b32 s9, s9, 0xb0
	s_add_i32 s8, s8, s5
	s_mul_hi_i32 s10, s8, 0x92492493
	s_add_i32 s10, s10, s8
	s_lshr_b32 s11, s10, 31
	s_ashr_i32 s10, s10, 6
	s_add_i32 s10, s10, s11
	s_mul_i32 s11, s10, 0x70
	s_sub_i32 s8, s8, s11
	s_bfe_i32 s11, s8, 0x80000
	s_bfe_u32 s11, s11, 0x3000c
	s_add_i32 s11, s8, s11
	s_and_b32 s12, s11, 0xf8
	s_add_i32 s7, s7, s5
	s_sub_i32 s8, s8, s12
	s_ashr_i32 s12, s7, 31
	s_mul_i32 s6, s6, s9
	s_lshr_b32 s12, s12, 26
	s_add_i32 s6, s6, s5
	s_add_i32 s12, s7, s12
	s_mul_hi_i32 s5, s6, 0x2e8ba2e9
	s_and_b32 s13, s12, 0xffc0
	s_lshr_b32 s9, s5, 31
	s_ashr_i32 s5, s5, 6
	s_sub_i32 s7, s7, s13
	s_add_i32 s5, s5, s9
	s_bfe_i32 s13, s7, 0x80000
	s_mul_i32 s9, s5, 0x160
	s_bfe_u32 s13, s13, 0x3000c
	s_sub_i32 s6, s6, s9
; __device__ __forceinline__ void mixer_phase256(const Args& A, int l, int vc, const bf16* Z, bf16* MIX, ss_t* ssa, ss_t* ssb, unsigned char* lds, int tid, int wid, int lane) {
;     bf16* KS = (bf16*)(lds + LDS_KS); bf16* VT = (bf16*)(lds + LDS_VT); float* BT = (float*)(lds + LDS_BT); bf16* VN = (bf16*)(lds + LDS_VN0);
;     const int gx = vc & 7, gj = vc >> 3;
;     const int n = 8 * gx + (gj >> 2), kvh = gj & 3, h = gj & 15, cb = 8 * gx + 4 * (gj >> 4);
;     const int fr = lane & 15, fq = lane >> 4;
;     const bool isK = tid < 256; const int arow = tid & 255; const int atok = (n - 1) * 128 + arow;
;     u32x4 aw[8], sw[8];
;     { const bf16* ap = Z + (size_t)(atok < 0 ? 0 : atok) * INW + (isK ? KCOL : VCOL) + kvh * 64;
; #pragma unroll
;       for (int c = 0; c < 8; ++c) aw[c] = *(const u32x4*)(ap + 8 * c); }
;     const int srow = tid & 127, sj = tid >> 7;
;     { const bf16* sp = Z + (size_t)((cb + sj) * 128 + srow) * INW + 1024 + h * 64;
; #pragma unroll
;       for (int c = 0; c < 8; ++c) sw[c] = *(const u32x4*)(sp + 8 * c); }
;     const int st = 16 * wid + fr; const int nks = (wid >> 1) + 1;
;     const float* wrow = A.sgu_w + ((size_t)(l * 16 + h) * 128 + st) * 128;
;     f32x4 wa[4][2];
; #pragma unroll
;     for (int ks = 0; ks < 4; ++ks) { wa[ks][0] = (f32x4){0.f, 0.f, 0.f, 0.f}; wa[ks][1] = wa[ks][0];
;         if (ks < nks) { wa[ks][0] = *(const f32x4*)(wrow + 32 * ks + 8 * fq); wa[ks][1] = *(const f32x4*)(wrow + 32 * ks + 8 * fq + 4); } }
;     const float sbias = A.sgu_b[(l * 16 + h) * 128 + st];
;     { const int g = tid >> 7, dist = tid & 127; BT[g * 128 + dist] = A.rel_bias[t5_bucket(dist) * 16 + kvh * 4 + g] * 1.4426950408889634f; }
; __global__ void __launch_bounds__(NWAVES * 64, 2) fwd_kernel(Args A) {
;     ...
;     for (int l = 0; l < DEPTH; ++l) {
;         { pg8::Gemm g{XB, (const bf16*)(ws + WS_WIN + l * SZ_WIN), SEQ, INW, DM};
;           pg8::EpiZ E{Z, INW, 8, SS + (size_t)(SS_Q1 + l) * SEQ};
;           if (G == 256) { pg8::OrderTok S{vc, INW / 256, 0}; pg8::gemm_phase<pg8::EpiZ, pg8::OrderTok, true, true>(ldsl, g, S, E); }
	s_add_i32 s13, s7, s13
	s_bfe_u32 s9, s6, 0x3001c
	s_and_b32 s14, s13, 0xf8
	s_add_i32 s9, s6, s9
	s_lshl_b32 s10, s10, 3
	s_sext_i32_i8 s8, s8
	s_sub_i32 s7, s7, s14
	s_and_b32 s14, s9, 0xfff8
	s_add_i32 s22, s10, s8
	s_ashr_i32 s8, s12, 6
	s_sub_i32 s6, s6, s14
	s_lshl_b32 s8, s8, 3
	s_sext_i32_i8 s7, s7
	s_add_i32 s12, s8, s7
	s_lshl_b32 s5, s5, 3
	s_sext_i32_i16 s7, s9
	s_sext_i32_i16 s6, s6
	s_add_i32 s26, s5, s6
	s_lshr_b32 s6, s7, 3
	s_ashr_i32 s5, s7, 3
	s_bfe_i64 s[6:7], s[6:7], 0x100000
	s_bfe_i32 s11, s11, 0x80000
	v_writelane_b32 v248, s5, 38
	s_lshl_b64 s[6:7], s[6:7], 20
	s_sext_i32_i16 s11, s11
	s_bfe_i32 s10, s13, 0x80000
	v_writelane_b32 v248, s6, 39
	s_sext_i32_i16 s10, s10
	s_ashr_i32 s5, s11, 3
	v_writelane_b32 v248, s7, 40
	v_writelane_b32 v248, s5, 41
	s_ashr_i32 s5, s10, 3
	v_writelane_b32 v248, s5, 42
	s_lshr_b32 s8, s10, 3
	s_mov_b32 s10, s26
	s_ashr_i32 s27, s26, 31
	s_lshr_b32 s6, s11, 3
	v_writelane_b32 v248, s10, 43
	s_mul_i32 s5, s85, s84
	s_mul_i32 s5, s5, s16
	v_writelane_b32 v248, s11, 44
	s_lshl_b64 s[10:11], s[26:27], 20
	s_add_u32 s10, s64, s10
	s_addc_u32 s11, s65, s11
	s_add_u32 s26, s10, 0x80000
	v_writelane_b32 v248, s10, 45
	s_addc_u32 s27, s11, 0
	s_bfe_i64 s[6:7], s[6:7], 0x100000
	v_writelane_b32 v248, s11, 46
	v_writelane_b32 v248, s26, 47
	s_lshl_b64 s[6:7], s[6:7], 20
	s_ashr_i32 s23, s22, 31
	v_writelane_b32 v248, s27, 48
	v_writelane_b32 v248, s6, 49
	s_movk_i32 s85, 0x1c00
	s_nop 0
	v_writelane_b32 v248, s7, 50
	s_mov_b32 s6, s22
	v_writelane_b32 v248, s6, 51
	s_nop 1
	v_writelane_b32 v248, s7, 52
	s_lshl_b64 s[6:7], s[22:23], 20
	s_add_u32 s6, s64, s6
	s_addc_u32 s7, s65, s7
	s_add_u32 s10, s6, 0x80000
	v_writelane_b32 v248, s6, 53
	s_addc_u32 s11, s7, 0
	s_ashr_i32 s13, s12, 31
	v_writelane_b32 v248, s7, 54
	v_writelane_b32 v248, s10, 55
	s_bfe_i64 s[6:7], s[8:9], 0x100000
	s_lshl_b64 s[6:7], s[6:7], 20
	v_writelane_b32 v248, s11, 56
	v_writelane_b32 v248, s6, 57
	s_nop 1
	v_writelane_b32 v248, s7, 58
	s_lshl_b64 s[6:7], s[12:13], 20
	s_add_u32 s6, s18, s6
	v_writelane_b32 v248, s18, 59
	s_addc_u32 s7, s19, s7
	s_add_u32 s8, s6, 0x80000
	v_writelane_b32 v248, s19, 60
	v_writelane_b32 v248, s5, 61
	v_writelane_b32 v248, s6, 62
	s_addc_u32 s9, s7, 0
	v_writelane_b32 v247, s8, 0
	v_writelane_b32 v248, s7, 63
	s_mov_b32 s6, s12
	v_writelane_b32 v247, s9, 1
	v_writelane_b32 v247, s6, 2
	s_mul_hi_i32 s5, s12, 0x2c0000
	s_nop 0
	v_writelane_b32 v247, s7, 3
	s_mul_i32 s6, s12, 0x2c0000
	s_add_u32 s6, s20, s6
	v_writelane_b32 v247, s20, 4
	s_addc_u32 s7, s21, s5
	s_add_u32 s8, s6, 0x160000
	v_writelane_b32 v247, s21, 5
	v_writelane_b32 v247, s6, 6
	s_addc_u32 s9, s7, 0
	s_and_b32 s3, s3, 7
	v_writelane_b32 v247, s7, 7
	s_lshl_b32 s5, s3, 22
	s_lshl_b32 s6, s4, 20
	s_or_b32 s5, s5, s6
	s_add_u32 s31, s86, s5
	s_addc_u32 s91, s87, 0
	v_writelane_b32 v247, s8, 8
	s_add_u32 s6, s31, 0x16280080
	s_addc_u32 s7, s91, 0
	v_writelane_b32 v247, s9, 9
	v_writelane_b32 v247, s6, 10
	s_add_u32 s5, s86, s24
	s_mul_i32 s3, s3, 0xb00000
	v_writelane_b32 v247, s7, 11
	v_writelane_b32 v247, s24, 12
	s_addc_u32 s6, s87, s25
	s_add_u32 s8, s5, 0x200100
	v_writelane_b32 v247, s25, 13
	s_addc_u32 s9, s6, 0
	v_writelane_b32 v247, s8, 14
	s_mul_i32 s4, s4, 0x2c0000
	s_nop 0
	v_writelane_b32 v247, s9, 15
	s_add_u32 s8, s31, 0x1ba80080
	s_addc_u32 s9, s91, 0
	v_writelane_b32 v247, s8, 16
	s_nop 1
	v_writelane_b32 v247, s9, 17
	s_add_u32 s8, s5, 0x3a00100
	s_addc_u32 s9, s6, 0
	s_add_i32 s3, s3, s4
	s_add_u32 s93, s86, s3
	s_addc_u32 s95, s87, 0
	v_writelane_b32 v247, s8, 18
	s_add_u32 s4, s93, 0x1db60080
	s_addc_u32 s5, s95, 0
	v_writelane_b32 v247, s9, 19
	v_writelane_b32 v247, s4, 20
	s_add_i32 s3, 0, 0x23ff0
	s_lshl_b32 s2, s2, 1
	v_writelane_b32 v247, s5, 21
	v_writelane_b32 v247, s3, 22
	s_add_i32 s3, 0, 0x23ff4
	v_writelane_b32 v247, s3, 23
	s_add_i32 s3, 0, 0x11400
	v_writelane_b32 v247, s3, 24
	v_writelane_b32 v247, s2, 25
	s_nop 1
	v_writelane_b32 v247, s3, 26
	s_add_i32 s2, 0, 0x11c00
	v_writelane_b32 v247, s2, 27
	v_writelane_b32 v247, s64, 28
	s_nop 1
	v_writelane_b32 v247, s65, 29
	v_writelane_b32 v247, s80, 30
	s_branch .LBB0_116

; #define PHASE_IDS() int tid = threadIdx.x; asm volatile("" : "+v"(tid)); const int lane = tid & 63, wid = __builtin_amdgcn_readfirstlane(tid >> 6), gw = bx * NWAVES + wid; (void)lane; (void)gw
; __device__ __forceinline__ void convert_items(const Args& A, unsigned char* ws, int g0, int g1, int w, int nw, float* scr, int lane) {
;     for (int it = g0 + w; it < g1; it += nw) {
; __global__ void __launch_bounds__(NWAVES * 64, 2) fwd_kernel(Args A) {
;     ...
;         if (G == 256 && vc >= 192) {
;             PHASE_IDS(); const int g0 = Q_P + l * (Q_G1 + Q_G3), g1 = g0 + Q_G1;
;             convert_items(A, ws, g0 < N_ALL ? g0 : N_ALL, g1 < N_ALL ? g1 : N_ALL, (vc - 192) * NWAVES + wid, 64 * NWAVES, (float*)(lds + wid * TSCR), lane); }
.LBB0_213:
	v_readlane_b32 s2, v250, 60
	v_readlane_b32 s3, v250, 61
	v_readlane_b32 s40, v250, 12
	s_andn2_b64 vcc, exec, s[2:3]
	s_mul_i32 s81, s78, 0x2faa
	v_readlane_b32 s42, v250, 14
	v_readlane_b32 s43, v250, 15
	v_readlane_b32 s44, v250, 16
	v_readlane_b32 s45, v250, 17
	v_readlane_b32 s46, v250, 18
	v_readlane_b32 s47, v250, 19
	v_readlane_b32 s48, v250, 20
	v_readlane_b32 s49, v250, 21
	v_readlane_b32 s50, v250, 22
	v_readlane_b32 s51, v250, 23
	v_readlane_b32 s52, v250, 24
	v_readlane_b32 s53, v250, 25
	v_readlane_b32 s54, v250, 26
	v_readlane_b32 s55, v250, 27
	v_readlane_b32 s41, v250, 13
	s_cbranch_vccnz .LBB0_249
	v_mov_b32_e32 v4, v204
	v_readlane_b32 s3, v250, 62
	v_readfirstlane_b32 s2, v4
	s_ashr_i32 s2, s2, 6
	s_add_i32 s3, s3, s81
	s_add_i32 s8, s81, 0x2102
	s_add_i32 s9, s3, s2
	s_cmp_ge_i32 s9, s8
	s_cbranch_scc1 .LBB0_249
	v_lshlrev_b32_e32 v0, 2, v4
	s_mulk_i32 s2, 0x4100
	v_bfe_u32 v1, v4, 4, 2
	v_and_b32_e32 v0, 60, v0
	s_add_i32 s2, s2, 0
	v_lshlrev_b32_e32 v3, 2, v0
	s_waitcnt lgkmcnt(0)
	v_mul_u32_u24_e32 v5, 0x104, v1
	v_add3_u32 v3, s2, v3, v5
	v_and_b32_e32 v5, 7, v4
	v_bfe_u32 v13, v4, 3, 3
	v_lshlrev_b32_e32 v12, 3, v5
	v_mul_u32_u24_e32 v4, 0x820, v5
	v_lshlrev_b32_e32 v5, 2, v13
	v_add3_u32 v16, s2, v4, v5
	v_or_b32_e32 v17, 8, v13
	v_or_b32_e32 v18, 16, v13
	v_or_b32_e32 v19, 24, v13
	v_or_b32_e32 v20, 32, v13
	v_or_b32_e32 v21, 40, v13
	v_or_b32_e32 v22, 48, v13
	v_or_b32_e32 v23, 56, v13
	s_lshl_b32 s10, s9, 6
	s_lshl_b32 s11, s9, 1
	s_branch .LBB0_219

; #define PHASE_IDS() int tid = threadIdx.x; asm volatile("" : "+v"(tid)); const int lane = tid & 63, wid = __builtin_amdgcn_readfirstlane(tid >> 6), gw = bx * NWAVES + wid; (void)lane; (void)gw
; __device__ __forceinline__ void convert_items(const Args& A, unsigned char* ws, int g0, int g1, int w, int nw, float* scr, int lane) {
;     for (int it = g0 + w; it < g1; it += nw) {
; __global__ void __launch_bounds__(NWAVES * 64, 2) fwd_kernel(Args A) {
;     ...
;         if (G == 256 && vc >= 128) {
;             PHASE_IDS(); const int g0 = Q_P + l * (Q_G1 + Q_G3) + Q_G1, g1 = g0 + Q_G3;
;             convert_items(A, ws, g0 < N_ALL ? g0 : N_ALL, g1 < N_ALL ? g1 : N_ALL, (vc - 128) * NWAVES + wid, 128 * NWAVES, (float*)(lds + wid * TSCR), lane); }
.LBB0_1058:
	v_readlane_b32 s2, v248, 33
	v_readlane_b32 s3, v248, 34
	v_readlane_b32 s40, v250, 12
	s_andn2_b64 vcc, exec, s[2:3]
	v_readlane_b32 s44, v250, 16
	v_readlane_b32 s45, v250, 17
	v_readlane_b32 s46, v250, 18
	v_readlane_b32 s47, v250, 19
	v_readlane_b32 s41, v250, 13
	v_readlane_b32 s42, v250, 14
	v_readlane_b32 s43, v250, 15
	v_readlane_b32 s48, v250, 20
	v_readlane_b32 s49, v250, 21
	v_readlane_b32 s50, v250, 22
	v_readlane_b32 s51, v250, 23
	v_readlane_b32 s52, v250, 24
	v_readlane_b32 s53, v250, 25
	v_readlane_b32 s54, v250, 26
	v_readlane_b32 s55, v250, 27
	s_cbranch_vccnz .LBB0_1094
	v_mov_b32_e32 v4, v204
	v_readlane_b32 s3, v248, 35
	v_readfirstlane_b32 s2, v4
	s_ashr_i32 s2, s2, 6
	s_min_u32 s8, s81, 0x7056
	s_add_i32 s3, s3, s81
	s_addk_i32 s8, 0x3faa
	s_add_i32 s9, s3, s2
	s_cmp_ge_i32 s9, s8
	s_cbranch_scc1 .LBB0_1094
	v_lshlrev_b32_e32 v0, 2, v4
	s_mulk_i32 s2, 0x4100
	v_bfe_u32 v1, v4, 4, 2
	v_and_b32_e32 v0, 60, v0
	s_add_i32 s2, s2, 0
	v_lshlrev_b32_e32 v3, 2, v0
	v_mul_u32_u24_e32 v5, 0x104, v1
	v_add3_u32 v3, s2, v3, v5
	v_and_b32_e32 v5, 7, v4
	v_bfe_u32 v13, v4, 3, 3
	v_lshlrev_b32_e32 v12, 3, v5
	v_mul_u32_u24_e32 v4, 0x820, v5
	v_lshlrev_b32_e32 v5, 2, v13
	v_add3_u32 v16, s2, v4, v5
	v_or_b32_e32 v17, 8, v13
	v_or_b32_e32 v18, 16, v13
	v_or_b32_e32 v19, 24, v13
	v_or_b32_e32 v20, 32, v13
	v_or_b32_e32 v21, 40, v13
	v_or_b32_e32 v22, 48, v13
	v_or_b32_e32 v23, 56, v13
	s_lshl_b32 s10, s9, 6
	s_lshl_b32 s11, s9, 1
	s_branch .LBB0_1064
